# gates_phase K loop: 16 operand loads per 8-step group issued together with counted waits (was load-wait-MFMA per step)
# baseline (speedup 1.0000x reference)
.LBB0_140:
	v_lshl_add_u64 v[18:19], v[12:13], 0, v[6:7]
	v_add_co_u32_e32 v26, vcc, 0x4000000, v18
	v_lshl_add_u64 v[28:29], v[14:15], 0, v[6:7]
	s_nop 0
	v_addc_co_u32_e32 v27, vcc, 0, v19, vcc
	global_load_dwordx4 v[40:43], v[26:27], off
	global_load_dwordx4 v[72:75], v[28:29], off offset:-256
	global_load_dwordx4 v[44:47], v[26:27], off offset:64
	global_load_dwordx4 v[76:79], v[28:29], off offset:-192
	global_load_dwordx4 v[48:51], v[26:27], off offset:128
	global_load_dwordx4 v[80:83], v[28:29], off offset:-128
	global_load_dwordx4 v[52:55], v[26:27], off offset:192
	global_load_dwordx4 v[84:87], v[28:29], off offset:-64
	global_load_dwordx4 v[56:59], v[26:27], off offset:256
	global_load_dwordx4 v[88:91], v[28:29], off
	global_load_dwordx4 v[60:63], v[26:27], off offset:320
	global_load_dwordx4 v[92:95], v[28:29], off offset:64
	global_load_dwordx4 v[64:67], v[26:27], off offset:384
	global_load_dwordx4 v[96:99], v[28:29], off offset:128
	global_load_dwordx4 v[68:71], v[26:27], off offset:448
	global_load_dwordx4 v[100:103], v[28:29], off offset:192
	s_addk_i32 s6, 0x100
	v_lshl_add_u64 v[12:13], v[12:13], 0, s[8:9]
	v_lshl_add_u64 v[14:15], v[14:15], 0, s[8:9]
	s_cmpk_gt_u32 s6, 0x3df
	s_waitcnt vmcnt(14)
	v_mfma_f32_16x16x32_bf16 v[0:3], v[40:43], v[72:75], v[0:3]
	s_waitcnt vmcnt(12)
	v_mfma_f32_16x16x32_bf16 v[0:3], v[44:47], v[76:79], v[0:3]
	s_waitcnt vmcnt(10)
	v_mfma_f32_16x16x32_bf16 v[0:3], v[48:51], v[80:83], v[0:3]
	s_waitcnt vmcnt(8)
	v_mfma_f32_16x16x32_bf16 v[0:3], v[52:55], v[84:87], v[0:3]
	s_waitcnt vmcnt(6)
	v_mfma_f32_16x16x32_bf16 v[0:3], v[56:59], v[88:91], v[0:3]
	s_waitcnt vmcnt(4)
	v_mfma_f32_16x16x32_bf16 v[0:3], v[60:63], v[92:95], v[0:3]
	s_waitcnt vmcnt(2)
	v_mfma_f32_16x16x32_bf16 v[0:3], v[64:67], v[96:99], v[0:3]
	s_waitcnt vmcnt(0)
	v_mfma_f32_16x16x32_bf16 v[0:3], v[68:71], v[100:103], v[0:3]
	s_cbranch_scc0 .LBB0_140
	v_lshl_or_b32 v12, v16, 4, v17
	v_ashrrev_i32_e32 v13, 31, v12
	v_lshlrev_b64 v[14:15], 6, v[12:13]
	v_lshl_add_u64 v[14:15], v[4:5], 0, v[14:15]
	s_nop 2
	global_store_dword v[14:15], v0, off
	v_or_b32_e32 v14, 1, v12
	v_ashrrev_i32_e32 v15, 31, v14
	v_lshlrev_b64 v[14:15], 6, v[14:15]
	v_lshl_add_u64 v[14:15], v[4:5], 0, v[14:15]
	v_or_b32_e32 v0, 2, v12
	global_store_dword v[14:15], v1, off
	v_ashrrev_i32_e32 v1, 31, v0
	v_lshlrev_b64 v[0:1], 6, v[0:1]
	v_lshl_add_u64 v[0:1], v[4:5], 0, v[0:1]
	global_store_dword v[0:1], v2, off
	v_or_b32_e32 v0, 3, v12
	v_ashrrev_i32_e32 v1, 31, v0
	v_add_u32_e32 v16, s78, v16
	s_movk_i32 s6, 0x3ff
	v_lshlrev_b64 v[0:1], 6, v[0:1]
	v_cmp_lt_i32_e32 vcc, s6, v16
	v_lshl_add_u64 v[0:1], v[4:5], 0, v[0:1]
	s_or_b64 s[4:5], vcc, s[4:5]
	v_add_u32_e32 v8, s64, v8
	global_store_dword v[0:1], v3, off
	s_andn2_b64 exec, exec, s[4:5]
	s_cbranch_execnz .LBB0_139
